# S5 prompt scan as two 128-token streams per wave (all lanes active, no hand-offs; A^128 combine in f32)
# speedup vs baseline: 1.1845x; 1.0011x over previous
; #define LAS __attribute__((address_space(3)))
; DI void s5_load_consts(S5C& K, const unsigned char* ws, int lg, int lane) {
;     const bf16_t* BBF = (const bf16_t*)(ws + WS_TAB + TB_BBF); const bf16_t* CF = (const bf16_t*)(ws + WS_TAB + TB_CF); const float* AB = (const float*)(ws + WS_TAB + TB_ABAR);
; #pragma unroll
;     for (int t = 0; t < 4; ++t) { K.bbf[t] = *(const bf16x8*)(BBF + (((size_t)lg * 4 + t) * 64 + lane) * 8); K.cf[t] = *(const bf16x8*)(CF + (((size_t)lg * 4 + t) * 64 + lane) * 8); }
; #pragma unroll
;     for (int st = 0; st < 2; ++st) { const int p = st * 32 + (lane & 31); K.are[st] = AB[((size_t)lg * 64 + p) * 2]; K.aim[st] = AB[((size_t)lg * 64 + p) * 2 + 1]; }
; }
; DI void s5_prompt_task(LAS unsigned char* lds, int task, int l, ArgsP a, const float* U, bf16_t* YC0, int tid) {
;     const int b = task >> 5, g = task & 31, lg = l * 32 + g, wave = tid >> 6, lane = tid & 63;
;     LAS bf16_t* Hs = (LAS bf16_t*)(lds + wave * 8704);
;     LAS float* Es = (LAS float*)(lds + 8 * 8704);
;     S5C K; s5_load_consts(K, a->ws, lg, lane);
;     const float* dvec = a->in[24] + l * 512 + g * 16;
;     const int rowb = b * 2048 + wave * 256;
;     float hre[2] = {0.f, 0.f}, him[2] = {0.f, 0.f};
.LBB0_900:
	s_and_b32 s42, s39, 31
	s_or_b32 s14, s42, s33
	s_ashr_i32 s15, s14, 31
	s_lshl_b64 s[30:31], s[14:15], 12
	v_lshl_or_b32 v0, v170, 1, s30
	v_mov_b32_e32 v1, s31
	v_lshl_add_u64 v[2:3], s[18:19], 0, v[0:1]
	s_ashr_i32 s43, s39, 5
	v_lshl_add_u64 v[4:5], s[20:21], 0, v[0:1]
	global_load_dwordx4 v[98:101], v[2:3], off
	global_load_dwordx4 v[102:105], v[4:5], off
	v_mov_b32_e32 v3, s31
	s_lshl_b64 s[30:31], s[14:15], 9
	v_or_b32_e32 v2, 0x400, v0
	s_add_u32 s14, s22, s30
	v_lshl_add_u64 v[4:5], s[18:19], 0, v[2:3]
	s_addc_u32 s15, s23, s31
	v_lshlrev_b32_e32 v6, 2, v171
	v_lshl_add_u64 v[2:3], s[20:21], 0, v[2:3]
	global_load_dwordx2 v[144:145], v6, s[14:15]
	global_load_dwordx2 v[150:151], v134, s[14:15]
	global_load_dwordx4 v[106:109], v[4:5], off
	global_load_dwordx4 v[110:113], v[2:3], off
	v_or_b32_e32 v2, 0x800, v0
	v_mov_b32_e32 v3, v1
	v_lshl_add_u64 v[4:5], s[18:19], 0, v[2:3]
	v_lshl_add_u64 v[2:3], s[20:21], 0, v[2:3]
	v_or_b32_e32 v0, 0xc00, v0
	global_load_dwordx4 v[114:117], v[4:5], off
	global_load_dwordx4 v[118:121], v[2:3], off
	v_lshl_add_u64 v[2:3], s[18:19], 0, v[0:1]
	v_lshl_add_u64 v[0:1], s[20:21], 0, v[0:1]
	global_load_dwordx4 v[122:125], v[2:3], off
	global_load_dwordx4 v[126:129], v[0:1], off
	s_lshl_b32 s45, s42, 4
	s_lshl_b32 s44, s43, 11
	s_lshl_b32 s14, s42, 6
	s_add_u32 s14, s4, s14
	v_mov_b32_e32 v143, v97
	v_mov_b32_e32 v96, v97
	v_add_u32_e32 v0, s44, v135
	s_addc_u32 s15, s5, 0
	s_mov_b32 s52, 0
	v_mov_b64_e32 v[78:79], v[96:97]
	v_and_b32_e32 v90, 4, v132
	v_lshrrev_b32_e32 v91, 1, v132
	v_lshlrev_b32_e32 v90, 5, v90
	v_and_b32_e32 v91, 12, v91
	v_and_b32_e32 v92, 3, v132
	v_or3_b32 v90, v90, v91, v92
	v_or_b32_e32 v179, v0, v90
	v_lshl_add_u64 v[64:65], s[14:15], 0, v[142:143]
	v_mov_b64_e32 v[80:81], v[96:97]
	s_movk_i32 s40, 0xcc0
	v_lshrrev_b32_e32 v91, 3, v172
	v_mad_u32_u24 v90, v91, s40, v173
	v_ashrrev_i32_e32 v1, 31, v179
	v_mov_b32_e32 v0, v179
	v_lshlrev_b64 v[0:1], 11, v[0:1]
	v_lshl_add_u64 v[4:5], v[64:65], 0, v[0:1]
	s_waitcnt vmcnt(0)
	global_load_dwordx4 v[198:201], v[4:5], off
	global_load_dwordx4 v[202:205], v[4:5], off offset:16
	v_pk_mov_b32 v[152:153], v[144:145], v[144:145] op_sel:[1,0]
	v_pk_mov_b32 v[154:155], v[150:151], v[150:151] op_sel:[1,0]
	v_mov_b64_e32 v[66:67], v[96:97]
	v_mov_b64_e32 v[68:69], v[96:97]
	v_mov_b32_e32 v240, v144
	v_mov_b32_e32 v241, v145
	v_mov_b32_e32 v244, v150
	v_mov_b32_e32 v245, v151
	v_mul_f32_e32 v0, v241, v241
	v_mul_f32_e32 v2, v245, v245
	v_add_f32_e32 v1, v240, v240
	v_add_f32_e32 v3, v244, v244
	v_mul_f32_e32 v241, v1, v241
	v_mul_f32_e32 v245, v3, v245
	v_fma_f32 v240, v240, v240, -v0
	v_fma_f32 v244, v244, v244, -v2
	v_mul_f32_e32 v0, v241, v241
	v_mul_f32_e32 v2, v245, v245
	v_add_f32_e32 v1, v240, v240
	v_add_f32_e32 v3, v244, v244
	v_mul_f32_e32 v241, v1, v241
	v_mul_f32_e32 v245, v3, v245
	v_fma_f32 v240, v240, v240, -v0
	v_fma_f32 v244, v244, v244, -v2
	v_mul_f32_e32 v0, v241, v241
	v_mul_f32_e32 v2, v245, v245
	v_add_f32_e32 v1, v240, v240
	v_add_f32_e32 v3, v244, v244
	v_mul_f32_e32 v241, v1, v241
	v_mul_f32_e32 v245, v3, v245
	v_fma_f32 v240, v240, v240, -v0
	v_fma_f32 v244, v244, v244, -v2
	v_mul_f32_e32 v0, v241, v241
	v_mul_f32_e32 v2, v245, v245
	v_add_f32_e32 v1, v240, v240
	v_add_f32_e32 v3, v244, v244
	v_mul_f32_e32 v241, v1, v241
	v_mul_f32_e32 v245, v3, v245
	v_fma_f32 v240, v240, v240, -v0
	v_fma_f32 v244, v244, v244, -v2
	v_mul_f32_e32 v0, v241, v241
	v_mul_f32_e32 v2, v245, v245
	v_add_f32_e32 v1, v240, v240
	v_add_f32_e32 v3, v244, v244
	v_mul_f32_e32 v241, v1, v241
	v_mul_f32_e32 v245, v3, v245
	v_fma_f32 v240, v240, v240, -v0
	v_fma_f32 v244, v244, v244, -v2
	v_mul_f32_e32 v0, v241, v241
	v_mul_f32_e32 v2, v245, v245
	v_add_f32_e32 v1, v240, v240
	v_add_f32_e32 v3, v244, v244
	v_mul_f32_e32 v241, v1, v241
	v_mul_f32_e32 v245, v3, v245
	v_fma_f32 v240, v240, v240, -v0
	v_fma_f32 v244, v244, v244, -v2
	v_mul_f32_e32 v0, v241, v241
	v_mul_f32_e32 v2, v245, v245
	v_add_f32_e32 v1, v240, v240
	v_add_f32_e32 v3, v244, v244
	v_mul_f32_e32 v241, v1, v241
	v_mul_f32_e32 v245, v3, v245
	v_fma_f32 v240, v240, v240, -v0
	v_fma_f32 v244, v244, v244, -v2
	v_mov_b32_e32 v242, v241
	v_mov_b32_e32 v243, v240
	v_mov_b32_e32 v246, v245
	v_mov_b32_e32 v247, v244
; DI bf16x8 pack8(const f32x4 a, const f32x4 b) { u32x4 p; p.x = cvt_pk_bf16(a[0], a[1]); p.y = cvt_pk_bf16(a[2], a[3]); p.z = cvt_pk_bf16(b[0], b[1]); p.w = cvt_pk_bf16(b[2], b[3]); return __builtin_bit_cast(bf16x8, p); }
; #define MFMA32(a, b, c) __builtin_amdgcn_mfma_f32_32x32x16_bf16((a), (b), (c), 0, 0, 0)
; template <bool OUT>
; DI void s5_tile(const S5C& K, const float* U, int row0, int g, int nruns, int nvalid, float (&hre)[2], float (&him)[2], LAS bf16_t* Hs, const float* dvec, bf16_t* YC0, int lane) {
;     ...
;     bf16x8 af = {0, 0, 0, 0, 0, 0, 0, 0};
;     if (tok < nvalid) { const float* up = U + (size_t)(row0 + tok) * 512 + g * 16 + half * 8; af = pack8(*(const f32x4*)up, *(const f32x4*)(up + 4)); }
;     f32x16 z16;
; #pragma unroll
;     for (int i = 0; i < 16; ++i) z16[i] = 0.f;
;     f32x16 dre[2], dim[2];
; #pragma unroll
;     for (int st = 0; st < 2; ++st) { dre[st] = MFMA32(af, K.bbf[st], z16); dim[st] = MFMA32(af, K.bbf[2 + st], z16); }
; #pragma unroll
;     for (int r = 0; r < 8; ++r) {
;         if (r < nruns) {
;             const int hf = r & 1, i0 = 4 * (r >> 1);
;             if (half == hf) {
; #pragma unroll
;                 for (int k = 0; k < 4; ++k)
; #pragma unroll
;                     for (int st = 0; st < 2; ++st) { const float nr = K.are[st] * hre[st] - K.aim[st] * him[st] + dre[st][i0 + k]; const float ni = K.are[st] * him[st] + K.aim[st] * hre[st] + dim[st][i0 + k];
;                         hre[st] = nr; him[st] = ni; dre[st][i0 + k] = nr; dim[st][i0 + k] = ni; }
;             }
; #pragma unroll
;             for (int st = 0; st < 2; ++st) { const float pr = __shfl_xor(hre[st], 32), pi = __shfl_xor(him[st], 32); if (half != hf) { hre[st] = pr; him[st] = pi; } }
.Ls5a_tile:
	s_waitcnt vmcnt(0)
	v_cvt_pk_bf16_f32 v86, v198, v199
	v_cvt_pk_bf16_f32 v87, v200, v201
	v_cvt_pk_bf16_f32 v88, v202, v203
	v_cvt_pk_bf16_f32 v89, v204, v205
	v_add_u32_e32 v92, s52, v179
	v_add_u32_e32 v92, 16, v92
	v_mfma_f32_32x32x16_bf16 v[0:15], v[86:89], v[98:101], 0
	v_mfma_f32_32x32x16_bf16 v[32:47], v[86:89], v[114:117], 0
	v_mfma_f32_32x32x16_bf16 v[16:31], v[86:89], v[106:109], 0
	v_mfma_f32_32x32x16_bf16 v[48:63], v[86:89], v[122:125], 0
	v_ashrrev_i32_e32 v93, 31, v92
	v_lshlrev_b64 v[92:93], 11, v[92:93]
	v_lshl_add_u64 v[92:93], v[64:65], 0, v[92:93]
	global_load_dwordx4 v[198:201], v[92:93], off
	global_load_dwordx4 v[202:205], v[92:93], off offset:16
	s_nop 0
	v_pk_mul_f32 v[70:71], v[152:153], v[66:67] op_sel:[0,1]
	v_pk_mul_f32 v[74:75], v[154:155], v[68:69] op_sel:[0,1]
	v_pk_fma_f32 v[72:73], v[144:145], v[66:67], v[70:71] op_sel_hi:[1,0,1] neg_lo:[0,0,1]
	v_pk_fma_f32 v[76:77], v[150:151], v[68:69], v[74:75] op_sel_hi:[1,0,1] neg_lo:[0,0,1]
	v_add_f32_e32 v0, v72, v0
	v_add_f32_e32 v32, v73, v32
	v_add_f32_e32 v16, v76, v16
	v_add_f32_e32 v48, v77, v48
	v_pk_mul_f32 v[70:71], v[152:153], v[32:33] op_sel_hi:[1,0]
	v_pk_mul_f32 v[74:75], v[154:155], v[48:49] op_sel_hi:[1,0]
	v_pk_fma_f32 v[72:73], v[144:145], v[0:1], v[70:71] op_sel_hi:[1,0,1] neg_lo:[0,0,1]
	v_pk_fma_f32 v[76:77], v[150:151], v[16:17], v[74:75] op_sel_hi:[1,0,1] neg_lo:[0,0,1]
	v_add_f32_e32 v1, v72, v1
	v_add_f32_e32 v33, v73, v33
	v_add_f32_e32 v17, v76, v17
	v_add_f32_e32 v49, v77, v49
	v_pk_mul_f32 v[70:71], v[152:153], v[32:33] op_sel:[0,1]
	v_pk_mul_f32 v[74:75], v[154:155], v[48:49] op_sel:[0,1]
	v_pk_fma_f32 v[72:73], v[144:145], v[0:1], v[70:71] op_sel:[0,1,0] neg_lo:[0,0,1]
	v_pk_fma_f32 v[76:77], v[150:151], v[16:17], v[74:75] op_sel:[0,1,0] neg_lo:[0,0,1]
	v_add_f32_e32 v2, v72, v2
	v_add_f32_e32 v34, v73, v34
	v_add_f32_e32 v18, v76, v18
	v_add_f32_e32 v50, v77, v50
	v_pk_mul_f32 v[70:71], v[152:153], v[34:35] op_sel_hi:[1,0]
	v_pk_mul_f32 v[74:75], v[154:155], v[50:51] op_sel_hi:[1,0]
	v_pk_fma_f32 v[72:73], v[144:145], v[2:3], v[70:71] op_sel_hi:[1,0,1] neg_lo:[0,0,1]
	v_pk_fma_f32 v[76:77], v[150:151], v[18:19], v[74:75] op_sel_hi:[1,0,1] neg_lo:[0,0,1]
	v_add_f32_e32 v3, v72, v3
	v_add_f32_e32 v35, v73, v35
	v_add_f32_e32 v19, v76, v19
	v_add_f32_e32 v51, v77, v51
	v_pk_mul_f32 v[70:71], v[152:153], v[34:35] op_sel:[0,1]
	v_pk_mul_f32 v[74:75], v[154:155], v[50:51] op_sel:[0,1]
	v_pk_fma_f32 v[72:73], v[144:145], v[2:3], v[70:71] op_sel:[0,1,0] neg_lo:[0,0,1]
	v_pk_fma_f32 v[76:77], v[150:151], v[18:19], v[74:75] op_sel:[0,1,0] neg_lo:[0,0,1]
	v_add_f32_e32 v4, v72, v4
	v_add_f32_e32 v36, v73, v36
	v_add_f32_e32 v20, v76, v20
	v_add_f32_e32 v52, v77, v52
	v_pk_mul_f32 v[70:71], v[152:153], v[36:37] op_sel_hi:[1,0]
	v_pk_mul_f32 v[74:75], v[154:155], v[52:53] op_sel_hi:[1,0]
	v_pk_fma_f32 v[72:73], v[144:145], v[4:5], v[70:71] op_sel_hi:[1,0,1] neg_lo:[0,0,1]
	v_pk_fma_f32 v[76:77], v[150:151], v[20:21], v[74:75] op_sel_hi:[1,0,1] neg_lo:[0,0,1]
	v_add_f32_e32 v5, v72, v5
	v_add_f32_e32 v37, v73, v37
	v_add_f32_e32 v21, v76, v21
	v_add_f32_e32 v53, v77, v53
	v_pk_mul_f32 v[70:71], v[152:153], v[36:37] op_sel:[0,1]
	v_pk_mul_f32 v[74:75], v[154:155], v[52:53] op_sel:[0,1]
	v_pk_fma_f32 v[72:73], v[144:145], v[4:5], v[70:71] op_sel:[0,1,0] neg_lo:[0,0,1]
	v_pk_fma_f32 v[76:77], v[150:151], v[20:21], v[74:75] op_sel:[0,1,0] neg_lo:[0,0,1]
	v_add_f32_e32 v6, v72, v6
	v_add_f32_e32 v38, v73, v38
	v_add_f32_e32 v22, v76, v22
	v_add_f32_e32 v54, v77, v54
	v_pk_mul_f32 v[70:71], v[152:153], v[38:39] op_sel_hi:[1,0]
	v_pk_mul_f32 v[74:75], v[154:155], v[54:55] op_sel_hi:[1,0]
	v_pk_fma_f32 v[72:73], v[144:145], v[6:7], v[70:71] op_sel_hi:[1,0,1] neg_lo:[0,0,1]
	v_pk_fma_f32 v[76:77], v[150:151], v[22:23], v[74:75] op_sel_hi:[1,0,1] neg_lo:[0,0,1]
	v_add_f32_e32 v7, v72, v7
	v_add_f32_e32 v39, v73, v39
	v_add_f32_e32 v23, v76, v23
	v_add_f32_e32 v55, v77, v55
	v_pk_mul_f32 v[70:71], v[152:153], v[38:39] op_sel:[0,1]
	v_pk_mul_f32 v[74:75], v[154:155], v[54:55] op_sel:[0,1]
; template <bool OUT>
; DI void s5_tile(const S5C& K, const float* U, int row0, int g, int nruns, int nvalid, float (&hre)[2], float (&him)[2], LAS bf16_t* Hs, const float* dvec, bf16_t* YC0, int lane) {
;     ...
;     for (int r = 0; r < 8; ++r) {
;         if (r < nruns) {
;             const int hf = r & 1, i0 = 4 * (r >> 1);
;             if (half == hf) {
; #pragma unroll
;                 for (int k = 0; k < 4; ++k)
; #pragma unroll
;                     for (int st = 0; st < 2; ++st) { const float nr = K.are[st] * hre[st] - K.aim[st] * him[st] + dre[st][i0 + k]; const float ni = K.are[st] * him[st] + K.aim[st] * hre[st] + dim[st][i0 + k];
;                         hre[st] = nr; him[st] = ni; dre[st][i0 + k] = nr; dim[st][i0 + k] = ni; }
;             }
; #pragma unroll
;             for (int st = 0; st < 2; ++st) { const float pr = __shfl_xor(hre[st], 32), pi = __shfl_xor(him[st], 32); if (half != hf) { hre[st] = pr; him[st] = pi; } }
; DI void s5_prompt_task(LAS unsigned char* lds, int task, int l, ArgsP a, const float* U, bf16_t* YC0, int tid) {
;     ...
;     { const float* A256 = (const float*)(a->ws + WS_TAB + TB_ABAR256); float pr[2], pi[2];
; #pragma unroll
;       for (int st = 0; st < 2; ++st) { const int p = st * 32 + (lane & 31); pr[st] = A256[((size_t)lg * 64 + p) * 2]; pi[st] = A256[((size_t)lg * 64 + p) * 2 + 1]; hre[st] = 0.f; him[st] = 0.f; }
;       for (int w = 0; w < wave; ++w) {
; #pragma unroll
;           for (int st = 0; st < 2; ++st) { const float er = Es[(w * 4 + st) * 32 + (lane & 31)], ei = Es[(w * 4 + 2 + st) * 32 + (lane & 31)];
;               const float nr = pr[st] * hre[st] - pi[st] * him[st] + er, ni = pr[st] * him[st] + pi[st] * hre[st] + ei; hre[st] = nr; him[st] = ni; } } }
	v_pk_fma_f32 v[72:73], v[144:145], v[6:7], v[70:71] op_sel:[0,1,0] neg_lo:[0,0,1]
	v_pk_fma_f32 v[76:77], v[150:151], v[22:23], v[74:75] op_sel:[0,1,0] neg_lo:[0,0,1]
	v_add_f32_e32 v8, v72, v8
	v_add_f32_e32 v40, v73, v40
	v_add_f32_e32 v24, v76, v24
	v_add_f32_e32 v56, v77, v56
	v_pk_mul_f32 v[70:71], v[152:153], v[40:41] op_sel_hi:[1,0]
	v_pk_mul_f32 v[74:75], v[154:155], v[56:57] op_sel_hi:[1,0]
	v_pk_fma_f32 v[72:73], v[144:145], v[8:9], v[70:71] op_sel_hi:[1,0,1] neg_lo:[0,0,1]
	v_pk_fma_f32 v[76:77], v[150:151], v[24:25], v[74:75] op_sel_hi:[1,0,1] neg_lo:[0,0,1]
	v_add_f32_e32 v9, v72, v9
	v_add_f32_e32 v41, v73, v41
	v_add_f32_e32 v25, v76, v25
	v_add_f32_e32 v57, v77, v57
	v_pk_mul_f32 v[70:71], v[152:153], v[40:41] op_sel:[0,1]
	v_pk_mul_f32 v[74:75], v[154:155], v[56:57] op_sel:[0,1]
	v_pk_fma_f32 v[72:73], v[144:145], v[8:9], v[70:71] op_sel:[0,1,0] neg_lo:[0,0,1]
	v_pk_fma_f32 v[76:77], v[150:151], v[24:25], v[74:75] op_sel:[0,1,0] neg_lo:[0,0,1]
	v_add_f32_e32 v10, v72, v10
	v_add_f32_e32 v42, v73, v42
	v_add_f32_e32 v26, v76, v26
	v_add_f32_e32 v58, v77, v58
	v_pk_mul_f32 v[70:71], v[152:153], v[42:43] op_sel_hi:[1,0]
	v_pk_mul_f32 v[74:75], v[154:155], v[58:59] op_sel_hi:[1,0]
	v_pk_fma_f32 v[72:73], v[144:145], v[10:11], v[70:71] op_sel_hi:[1,0,1] neg_lo:[0,0,1]
	v_pk_fma_f32 v[76:77], v[150:151], v[26:27], v[74:75] op_sel_hi:[1,0,1] neg_lo:[0,0,1]
	v_add_f32_e32 v11, v72, v11
	v_add_f32_e32 v43, v73, v43
	v_add_f32_e32 v27, v76, v27
	v_add_f32_e32 v59, v77, v59
	v_pk_mul_f32 v[70:71], v[152:153], v[42:43] op_sel:[0,1]
	v_pk_mul_f32 v[74:75], v[154:155], v[58:59] op_sel:[0,1]
	v_pk_fma_f32 v[72:73], v[144:145], v[10:11], v[70:71] op_sel:[0,1,0] neg_lo:[0,0,1]
	v_pk_fma_f32 v[76:77], v[150:151], v[26:27], v[74:75] op_sel:[0,1,0] neg_lo:[0,0,1]
	v_add_f32_e32 v12, v72, v12
	v_add_f32_e32 v44, v73, v44
	v_add_f32_e32 v28, v76, v28
	v_add_f32_e32 v60, v77, v60
	v_pk_mul_f32 v[70:71], v[152:153], v[44:45] op_sel_hi:[1,0]
	v_pk_mul_f32 v[74:75], v[154:155], v[60:61] op_sel_hi:[1,0]
	v_pk_fma_f32 v[72:73], v[144:145], v[12:13], v[70:71] op_sel_hi:[1,0,1] neg_lo:[0,0,1]
	v_pk_fma_f32 v[76:77], v[150:151], v[28:29], v[74:75] op_sel_hi:[1,0,1] neg_lo:[0,0,1]
	v_add_f32_e32 v13, v72, v13
	v_add_f32_e32 v45, v73, v45
	v_add_f32_e32 v29, v76, v29
	v_add_f32_e32 v61, v77, v61
	v_pk_mul_f32 v[70:71], v[152:153], v[44:45] op_sel:[0,1]
	v_pk_mul_f32 v[74:75], v[154:155], v[60:61] op_sel:[0,1]
	v_pk_fma_f32 v[72:73], v[144:145], v[12:13], v[70:71] op_sel:[0,1,0] neg_lo:[0,0,1]
	v_pk_fma_f32 v[76:77], v[150:151], v[28:29], v[74:75] op_sel:[0,1,0] neg_lo:[0,0,1]
	v_add_f32_e32 v14, v72, v14
	v_add_f32_e32 v46, v73, v46
	v_add_f32_e32 v30, v76, v30
	v_add_f32_e32 v62, v77, v62
	v_pk_mul_f32 v[70:71], v[152:153], v[46:47] op_sel_hi:[1,0]
	v_pk_mul_f32 v[74:75], v[154:155], v[62:63] op_sel_hi:[1,0]
	v_pk_fma_f32 v[72:73], v[144:145], v[14:15], v[70:71] op_sel_hi:[1,0,1] neg_lo:[0,0,1]
	v_pk_fma_f32 v[76:77], v[150:151], v[30:31], v[74:75] op_sel_hi:[1,0,1] neg_lo:[0,0,1]
	v_add_f32_e32 v15, v72, v15
	v_add_f32_e32 v47, v73, v47
	v_add_f32_e32 v31, v76, v31
	v_add_f32_e32 v63, v77, v63
	v_mov_b32_e32 v66, v15
	v_mov_b32_e32 v67, v47
	v_mov_b32_e32 v68, v31
	v_mov_b32_e32 v69, v63
	s_add_i32 s52, s52, 16
	s_cmpk_eq_i32 s52, 0x80
	s_cbranch_scc0 .Ls5a_tile
	v_mov_b64_e32 v[236:237], v[66:67]
	v_mov_b64_e32 v[238:239], v[68:69]
	v_mov_b64_e32 v[82:83], v[66:67]
	v_mov_b64_e32 v[84:85], v[68:69]
	s_nop 1
	v_permlane32_swap_b32_e32 v236, v82
	v_permlane32_swap_b32_e32 v237, v83
	v_permlane32_swap_b32_e32 v238, v84
	v_permlane32_swap_b32_e32 v239, v85
	s_nop 0
	v_pk_mul_f32 v[70:71], v[242:243], v[236:237] op_sel:[0,1]
	v_pk_mul_f32 v[74:75], v[246:247], v[238:239] op_sel:[0,1]
	v_pk_fma_f32 v[72:73], v[240:241], v[236:237], v[70:71] op_sel_hi:[1,0,1] neg_lo:[0,0,1]
	v_pk_fma_f32 v[76:77], v[244:245], v[238:239], v[74:75] op_sel_hi:[1,0,1] neg_lo:[0,0,1]
	v_pk_add_f32 v[72:73], v[72:73], v[82:83]
	v_pk_add_f32 v[76:77], v[76:77], v[84:85]
	v_mov_b32_e32 v78, v72
	v_mov_b32_e32 v79, v76
	v_mov_b32_e32 v80, v73
	v_mov_b32_e32 v81, v77

; #define LAS __attribute__((address_space(3)))
; DI bf16x8 pack8(const f32x4 a, const f32x4 b) { u32x4 p; p.x = cvt_pk_bf16(a[0], a[1]); p.y = cvt_pk_bf16(a[2], a[3]); p.z = cvt_pk_bf16(b[0], b[1]); p.w = cvt_pk_bf16(b[2], b[3]); return __builtin_bit_cast(bf16x8, p); }
; #define MFMA32(a, b, c) __builtin_amdgcn_mfma_f32_32x32x16_bf16((a), (b), (c), 0, 0, 0)
; template <bool OUT>
; DI void s5_tile(const S5C& K, const float* U, int row0, int g, int nruns, int nvalid, float (&hre)[2], float (&him)[2], LAS bf16_t* Hs, const float* dvec, bf16_t* YC0, int lane) {
;     const int tok = lane & 31, half = lane >> 5;
;     bf16x8 af = {0, 0, 0, 0, 0, 0, 0, 0};
;     if (tok < nvalid) { const float* up = U + (size_t)(row0 + tok) * 512 + g * 16 + half * 8; af = pack8(*(const f32x4*)up, *(const f32x4*)(up + 4)); }
;     f32x16 z16;
; #pragma unroll
;     for (int i = 0; i < 16; ++i) z16[i] = 0.f;
;     f32x16 dre[2], dim[2];
; #pragma unroll
;     for (int st = 0; st < 2; ++st) { dre[st] = MFMA32(af, K.bbf[st], z16); dim[st] = MFMA32(af, K.bbf[2 + st], z16); }
; #pragma unroll
;     for (int r = 0; r < 8; ++r) {
;         if (r < nruns) {
;             const int hf = r & 1, i0 = 4 * (r >> 1);
;             if (half == hf) {
; #pragma unroll
;                 for (int k = 0; k < 4; ++k)
; #pragma unroll
;                     for (int st = 0; st < 2; ++st) { const float nr = K.are[st] * hre[st] - K.aim[st] * him[st] + dre[st][i0 + k]; const float ni = K.are[st] * him[st] + K.aim[st] * hre[st] + dim[st][i0 + k];
;                         hre[st] = nr; him[st] = ni; dre[st][i0 + k] = nr; dim[st][i0 + k] = ni; }
;             }
; #pragma unroll
;             for (int st = 0; st < 2; ++st) { const float pr = __shfl_xor(hre[st], 32), pi = __shfl_xor(him[st], 32); if (half != hf) { hre[st] = pr; him[st] = pi; } }
; DI void s5_prompt_task(LAS unsigned char* lds, int task, int l, ArgsP a, const float* U, bf16_t* YC0, int tid) {
;     ...
;     for (int tl = 0; tl < 8; ++tl) s5_tile<true>(K, U, rowb + tl * 32, g, 8, 32, hre, him, Hs, dvec, YC0, lane);
.LBB0_932:
	s_or_b64 exec, exec, s[40:41]
	v_lshlrev_b32_e32 v0, 2, v172
	v_mov_b32_e32 v1, v97
	s_lshl_b32 s56, s45, 2
	v_lshl_add_u64 v[158:159], s[14:15], 0, v[0:1]
	v_or_b32_e32 v96, s45, v175
	v_lshl_add_u64 v[160:161], v[140:141], 0, s[56:57]
	v_add_u32_e32 v180, s44, v177
	s_mov_b32 s30, 0
	v_ashrrev_i32_e32 v1, 31, v179
	v_mov_b32_e32 v0, v179
	v_lshlrev_b64 v[0:1], 11, v[0:1]
	v_lshl_add_u64 v[4:5], v[158:159], 0, v[0:1]
	global_load_dwordx4 v[206:209], v[4:5], off
	global_load_dwordx4 v[210:213], v[4:5], off offset:16
	v_mov_b32_e32 v82, v164
	v_mov_b32_e32 v83, v162
	v_mov_b32_e32 v84, v165
	v_mov_b32_e32 v85, v163
	v_pk_mul_f32 v[70:71], v[242:243], v[82:83] op_sel:[0,1]
	v_pk_mul_f32 v[74:75], v[246:247], v[84:85] op_sel:[0,1]
	v_pk_fma_f32 v[72:73], v[240:241], v[82:83], v[70:71] op_sel_hi:[1,0,1] neg_lo:[0,0,1]
	v_pk_fma_f32 v[76:77], v[244:245], v[84:85], v[74:75] op_sel_hi:[1,0,1] neg_lo:[0,0,1]
	v_pk_add_f32 v[72:73], v[72:73], v[236:237]
	v_pk_add_f32 v[76:77], v[76:77], v[238:239]
	v_mov_b64_e32 v[66:67], v[82:83]
	v_mov_b64_e32 v[68:69], v[84:85]
	s_mov_b64 exec, s[8:9]
	v_mov_b64_e32 v[66:67], v[72:73]
	v_mov_b64_e32 v[68:69], v[76:77]
	s_mov_b64 exec, -1
	v_add_u32_e32 v94, v174, v176
	s_waitcnt vmcnt(0)
.Ls5b_tile:
	v_cvt_pk_bf16_f32 v86, v206, v207
	v_cvt_pk_bf16_f32 v87, v208, v209
	v_cvt_pk_bf16_f32 v88, v210, v211
	v_cvt_pk_bf16_f32 v89, v212, v213
	v_add_u32_e32 v92, s30, v179
	v_add_u32_e32 v92, 16, v92
	v_mfma_f32_32x32x16_bf16 v[0:15], v[86:89], v[98:101], 0
	v_mfma_f32_32x32x16_bf16 v[32:47], v[86:89], v[114:117], 0
	v_mfma_f32_32x32x16_bf16 v[16:31], v[86:89], v[106:109], 0
	v_mfma_f32_32x32x16_bf16 v[48:63], v[86:89], v[122:125], 0
	v_add_u32_e32 v226, s30, v180
	v_ashrrev_i32_e32 v227, 31, v226
	v_lshlrev_b64 v[228:229], 9, v[226:227]
	v_or_b32_e32 v228, v228, v96
	v_lshl_add_u64 v[230:231], v[228:229], 1, s[16:17]
	v_lshl_add_u64 v[228:229], v[228:229], 2, s[4:5]
	global_load_dwordx4 v[214:217], v[228:229], off
	v_add_u32_e32 v226, 0x80, v226
	v_ashrrev_i32_e32 v227, 31, v226
	v_lshlrev_b64 v[228:229], 9, v[226:227]
	v_or_b32_e32 v228, v228, v96
	v_lshl_add_u64 v[232:233], v[228:229], 1, s[16:17]
	v_lshl_add_u64 v[228:229], v[228:229], 2, s[4:5]
	global_load_dwordx4 v[218:221], v[228:229], off
	global_load_dwordx4 v[222:225], v[160:161], off
	v_ashrrev_i32_e32 v93, 31, v92
	v_lshlrev_b64 v[92:93], 11, v[92:93]
	v_lshl_add_u64 v[92:93], v[158:159], 0, v[92:93]
	global_load_dwordx4 v[206:209], v[92:93], off
	global_load_dwordx4 v[210:213], v[92:93], off offset:16
	v_pk_mul_f32 v[70:71], v[152:153], v[66:67] op_sel:[0,1]
	v_pk_mul_f32 v[74:75], v[154:155], v[68:69] op_sel:[0,1]
	v_pk_fma_f32 v[72:73], v[144:145], v[66:67], v[70:71] op_sel_hi:[1,0,1] neg_lo:[0,0,1]
	v_pk_fma_f32 v[76:77], v[150:151], v[68:69], v[74:75] op_sel_hi:[1,0,1] neg_lo:[0,0,1]
	v_add_f32_e32 v0, v72, v0
	v_add_f32_e32 v32, v73, v32
	v_add_f32_e32 v16, v76, v16
	v_add_f32_e32 v48, v77, v48
	v_pk_mul_f32 v[70:71], v[152:153], v[32:33] op_sel_hi:[1,0]
	v_pk_mul_f32 v[74:75], v[154:155], v[48:49] op_sel_hi:[1,0]
	v_pk_fma_f32 v[72:73], v[144:145], v[0:1], v[70:71] op_sel_hi:[1,0,1] neg_lo:[0,0,1]
	v_pk_fma_f32 v[76:77], v[150:151], v[16:17], v[74:75] op_sel_hi:[1,0,1] neg_lo:[0,0,1]
	v_add_f32_e32 v1, v72, v1
	v_add_f32_e32 v33, v73, v33
	v_add_f32_e32 v17, v76, v17
	v_add_f32_e32 v49, v77, v49
	v_pk_mul_f32 v[70:71], v[152:153], v[32:33] op_sel:[0,1]
	v_pk_mul_f32 v[74:75], v[154:155], v[48:49] op_sel:[0,1]
	v_pk_fma_f32 v[72:73], v[144:145], v[0:1], v[70:71] op_sel:[0,1,0] neg_lo:[0,0,1]
	v_pk_fma_f32 v[76:77], v[150:151], v[16:17], v[74:75] op_sel:[0,1,0] neg_lo:[0,0,1]
	v_add_f32_e32 v2, v72, v2
	v_add_f32_e32 v34, v73, v34
	v_add_f32_e32 v18, v76, v18
	v_add_f32_e32 v50, v77, v50
	v_pk_mul_f32 v[70:71], v[152:153], v[34:35] op_sel_hi:[1,0]
	v_pk_mul_f32 v[74:75], v[154:155], v[50:51] op_sel_hi:[1,0]
	v_pk_fma_f32 v[72:73], v[144:145], v[2:3], v[70:71] op_sel_hi:[1,0,1] neg_lo:[0,0,1]
	v_pk_fma_f32 v[76:77], v[150:151], v[18:19], v[74:75] op_sel_hi:[1,0,1] neg_lo:[0,0,1]
	v_add_f32_e32 v3, v72, v3
	v_add_f32_e32 v35, v73, v35
	v_add_f32_e32 v19, v76, v19
	v_add_f32_e32 v51, v77, v51
	v_pk_mul_f32 v[70:71], v[152:153], v[34:35] op_sel:[0,1]
	v_pk_mul_f32 v[74:75], v[154:155], v[50:51] op_sel:[0,1]
	v_pk_fma_f32 v[72:73], v[144:145], v[2:3], v[70:71] op_sel:[0,1,0] neg_lo:[0,0,1]
	v_pk_fma_f32 v[76:77], v[150:151], v[18:19], v[74:75] op_sel:[0,1,0] neg_lo:[0,0,1]
	v_add_f32_e32 v4, v72, v4
	v_add_f32_e32 v36, v73, v36
	v_add_f32_e32 v20, v76, v20
	v_add_f32_e32 v52, v77, v52
	v_pk_mul_f32 v[70:71], v[152:153], v[36:37] op_sel_hi:[1,0]
	v_pk_mul_f32 v[74:75], v[154:155], v[52:53] op_sel_hi:[1,0]
	v_pk_fma_f32 v[72:73], v[144:145], v[4:5], v[70:71] op_sel_hi:[1,0,1] neg_lo:[0,0,1]
	v_pk_fma_f32 v[76:77], v[150:151], v[20:21], v[74:75] op_sel_hi:[1,0,1] neg_lo:[0,0,1]
	v_add_f32_e32 v5, v72, v5
	v_add_f32_e32 v37, v73, v37
	v_add_f32_e32 v21, v76, v21
	v_add_f32_e32 v53, v77, v53
	v_pk_mul_f32 v[70:71], v[152:153], v[36:37] op_sel:[0,1]
	v_pk_mul_f32 v[74:75], v[154:155], v[52:53] op_sel:[0,1]
	v_pk_fma_f32 v[72:73], v[144:145], v[4:5], v[70:71] op_sel:[0,1,0] neg_lo:[0,0,1]
	v_pk_fma_f32 v[76:77], v[150:151], v[20:21], v[74:75] op_sel:[0,1,0] neg_lo:[0,0,1]
	v_add_f32_e32 v6, v72, v6
	v_add_f32_e32 v38, v73, v38
	v_add_f32_e32 v22, v76, v22
	v_add_f32_e32 v54, v77, v54
	v_pk_mul_f32 v[70:71], v[152:153], v[38:39] op_sel_hi:[1,0]
	v_pk_mul_f32 v[74:75], v[154:155], v[54:55] op_sel_hi:[1,0]
	v_pk_fma_f32 v[72:73], v[144:145], v[6:7], v[70:71] op_sel_hi:[1,0,1] neg_lo:[0,0,1]
	v_pk_fma_f32 v[76:77], v[150:151], v[22:23], v[74:75] op_sel_hi:[1,0,1] neg_lo:[0,0,1]
; #define LAS __attribute__((address_space(3)))
; DI unsigned f2bf(float f) { unsigned u = __float_as_uint(f); return (u + 0x7fffu + ((u >> 16) & 1u)) >> 16; }
; template <bool OUT>
; DI void s5_tile(const S5C& K, const float* U, int row0, int g, int nruns, int nvalid, float (&hre)[2], float (&him)[2], LAS bf16_t* Hs, const float* dvec, bf16_t* YC0, int lane) {
;     ...
;                     for (int st = 0; st < 2; ++st) { const float nr = K.are[st] * hre[st] - K.aim[st] * him[st] + dre[st][i0 + k]; const float ni = K.are[st] * him[st] + K.aim[st] * hre[st] + dim[st][i0 + k];
;                         hre[st] = nr; him[st] = ni; dre[st][i0 + k] = nr; dim[st][i0 + k] = ni; }
;             }
; #pragma unroll
;             for (int st = 0; st < 2; ++st) { const float pr = __shfl_xor(hre[st], 32), pi = __shfl_xor(him[st], 32); if (half != hf) { hre[st] = pr; him[st] = pi; } }
;         }
;     }
;     if (OUT) {
; #pragma unroll
;         for (int i = 0; i < 16; ++i) { const int tr = (i & 3) + 8 * (i >> 2) + 4 * half; LAS bf16_t* hp = Hs + tr * 136 + tok;
; #pragma unroll
;             for (int st = 0; st < 2; ++st) { hp[st * 32] = (bf16_t)f2bf(dre[st][i]); hp[64 + st * 32] = (bf16_t)f2bf(dim[st][i]); } }
	v_add_f32_e32 v7, v72, v7
	v_add_f32_e32 v39, v73, v39
	v_add_f32_e32 v23, v76, v23
	v_add_f32_e32 v55, v77, v55
	v_pk_mul_f32 v[70:71], v[152:153], v[38:39] op_sel:[0,1]
	v_pk_mul_f32 v[74:75], v[154:155], v[54:55] op_sel:[0,1]
	v_pk_fma_f32 v[72:73], v[144:145], v[6:7], v[70:71] op_sel:[0,1,0] neg_lo:[0,0,1]
	v_pk_fma_f32 v[76:77], v[150:151], v[22:23], v[74:75] op_sel:[0,1,0] neg_lo:[0,0,1]
	v_add_f32_e32 v8, v72, v8
	v_add_f32_e32 v40, v73, v40
	v_add_f32_e32 v24, v76, v24
	v_add_f32_e32 v56, v77, v56
	v_pk_mul_f32 v[70:71], v[152:153], v[40:41] op_sel_hi:[1,0]
	v_pk_mul_f32 v[74:75], v[154:155], v[56:57] op_sel_hi:[1,0]
	v_pk_fma_f32 v[72:73], v[144:145], v[8:9], v[70:71] op_sel_hi:[1,0,1] neg_lo:[0,0,1]
	v_pk_fma_f32 v[76:77], v[150:151], v[24:25], v[74:75] op_sel_hi:[1,0,1] neg_lo:[0,0,1]
	v_add_f32_e32 v9, v72, v9
	v_add_f32_e32 v41, v73, v41
	v_add_f32_e32 v25, v76, v25
	v_add_f32_e32 v57, v77, v57
	v_pk_mul_f32 v[70:71], v[152:153], v[40:41] op_sel:[0,1]
	v_pk_mul_f32 v[74:75], v[154:155], v[56:57] op_sel:[0,1]
	v_pk_fma_f32 v[72:73], v[144:145], v[8:9], v[70:71] op_sel:[0,1,0] neg_lo:[0,0,1]
	v_pk_fma_f32 v[76:77], v[150:151], v[24:25], v[74:75] op_sel:[0,1,0] neg_lo:[0,0,1]
	v_add_f32_e32 v10, v72, v10
	v_add_f32_e32 v42, v73, v42
	v_add_f32_e32 v26, v76, v26
	v_add_f32_e32 v58, v77, v58
	v_pk_mul_f32 v[70:71], v[152:153], v[42:43] op_sel_hi:[1,0]
	v_pk_mul_f32 v[74:75], v[154:155], v[58:59] op_sel_hi:[1,0]
	v_pk_fma_f32 v[72:73], v[144:145], v[10:11], v[70:71] op_sel_hi:[1,0,1] neg_lo:[0,0,1]
	v_pk_fma_f32 v[76:77], v[150:151], v[26:27], v[74:75] op_sel_hi:[1,0,1] neg_lo:[0,0,1]
	v_add_f32_e32 v11, v72, v11
	v_add_f32_e32 v43, v73, v43
	v_add_f32_e32 v27, v76, v27
	v_add_f32_e32 v59, v77, v59
	v_pk_mul_f32 v[70:71], v[152:153], v[42:43] op_sel:[0,1]
	v_pk_mul_f32 v[74:75], v[154:155], v[58:59] op_sel:[0,1]
	v_pk_fma_f32 v[72:73], v[144:145], v[10:11], v[70:71] op_sel:[0,1,0] neg_lo:[0,0,1]
	v_pk_fma_f32 v[76:77], v[150:151], v[26:27], v[74:75] op_sel:[0,1,0] neg_lo:[0,0,1]
	v_add_f32_e32 v12, v72, v12
	v_add_f32_e32 v44, v73, v44
	v_add_f32_e32 v28, v76, v28
	v_add_f32_e32 v60, v77, v60
	v_pk_mul_f32 v[70:71], v[152:153], v[44:45] op_sel_hi:[1,0]
	v_pk_mul_f32 v[74:75], v[154:155], v[60:61] op_sel_hi:[1,0]
	v_pk_fma_f32 v[72:73], v[144:145], v[12:13], v[70:71] op_sel_hi:[1,0,1] neg_lo:[0,0,1]
	v_pk_fma_f32 v[76:77], v[150:151], v[28:29], v[74:75] op_sel_hi:[1,0,1] neg_lo:[0,0,1]
	v_add_f32_e32 v13, v72, v13
	v_add_f32_e32 v45, v73, v45
	v_add_f32_e32 v29, v76, v29
	v_add_f32_e32 v61, v77, v61
	v_pk_mul_f32 v[70:71], v[152:153], v[44:45] op_sel:[0,1]
	v_pk_mul_f32 v[74:75], v[154:155], v[60:61] op_sel:[0,1]
	v_pk_fma_f32 v[72:73], v[144:145], v[12:13], v[70:71] op_sel:[0,1,0] neg_lo:[0,0,1]
	v_pk_fma_f32 v[76:77], v[150:151], v[28:29], v[74:75] op_sel:[0,1,0] neg_lo:[0,0,1]
	v_add_f32_e32 v14, v72, v14
	v_add_f32_e32 v46, v73, v46
	v_add_f32_e32 v30, v76, v30
	v_add_f32_e32 v62, v77, v62
	v_pk_mul_f32 v[70:71], v[152:153], v[46:47] op_sel_hi:[1,0]
	v_pk_mul_f32 v[74:75], v[154:155], v[62:63] op_sel_hi:[1,0]
	v_pk_fma_f32 v[72:73], v[144:145], v[14:15], v[70:71] op_sel_hi:[1,0,1] neg_lo:[0,0,1]
	v_pk_fma_f32 v[76:77], v[150:151], v[30:31], v[74:75] op_sel_hi:[1,0,1] neg_lo:[0,0,1]
	v_add_f32_e32 v15, v72, v15
	v_add_f32_e32 v47, v73, v47
	v_add_f32_e32 v31, v76, v31
	v_add_f32_e32 v63, v77, v63
	v_mov_b32_e32 v66, v15
	v_mov_b32_e32 v67, v47
	v_mov_b32_e32 v68, v31
	v_mov_b32_e32 v69, v63
	v_cvt_pk_bf16_f32 v82, v0, v32
	v_cvt_pk_bf16_f32 v83, v16, v48
	ds_write_b16 v90, v82
	ds_write_b16_d16_hi v90, v82 offset:128
	ds_write_b16 v90, v83 offset:64
	ds_write_b16_d16_hi v90, v83 offset:192
	v_cvt_pk_bf16_f32 v84, v1, v33
	v_cvt_pk_bf16_f32 v85, v17, v49
	ds_write_b16 v90, v84 offset:272
	ds_write_b16_d16_hi v90, v84 offset:400
	ds_write_b16 v90, v85 offset:336
	ds_write_b16_d16_hi v90, v85 offset:464
	v_cvt_pk_bf16_f32 v82, v2, v34
	v_cvt_pk_bf16_f32 v83, v18, v50
	ds_write_b16 v90, v82 offset:544
	ds_write_b16_d16_hi v90, v82 offset:672
	ds_write_b16 v90, v83 offset:608
	ds_write_b16_d16_hi v90, v83 offset:736
	v_cvt_pk_bf16_f32 v84, v3, v35
	v_cvt_pk_bf16_f32 v85, v19, v51
	ds_write_b16 v90, v84 offset:816
	ds_write_b16_d16_hi v90, v84 offset:944
	ds_write_b16 v90, v85 offset:880
	ds_write_b16_d16_hi v90, v85 offset:1008
	v_cvt_pk_bf16_f32 v82, v4, v36
	v_cvt_pk_bf16_f32 v83, v20, v52
	ds_write_b16 v90, v82 offset:1088
	ds_write_b16_d16_hi v90, v82 offset:1216
	ds_write_b16 v90, v83 offset:1152
	ds_write_b16_d16_hi v90, v83 offset:1280
	v_cvt_pk_bf16_f32 v84, v5, v37
	v_cvt_pk_bf16_f32 v85, v21, v53
	ds_write_b16 v90, v84 offset:1360
	ds_write_b16_d16_hi v90, v84 offset:1488
	ds_write_b16 v90, v85 offset:1424
	ds_write_b16_d16_hi v90, v85 offset:1552
	v_cvt_pk_bf16_f32 v82, v6, v38
	v_cvt_pk_bf16_f32 v83, v22, v54
	ds_write_b16 v90, v82 offset:1632
	ds_write_b16_d16_hi v90, v82 offset:1760
	ds_write_b16 v90, v83 offset:1696
	ds_write_b16_d16_hi v90, v83 offset:1824
	v_cvt_pk_bf16_f32 v84, v7, v39
	v_cvt_pk_bf16_f32 v85, v23, v55
	ds_write_b16 v90, v84 offset:1904
	ds_write_b16_d16_hi v90, v84 offset:2032
	ds_write_b16 v90, v85 offset:1968
	ds_write_b16_d16_hi v90, v85 offset:2096
	v_cvt_pk_bf16_f32 v82, v8, v40
	v_cvt_pk_bf16_f32 v83, v24, v56
	ds_write_b16 v90, v82 offset:2176
	ds_write_b16_d16_hi v90, v82 offset:2304
	ds_write_b16 v90, v83 offset:2240
	ds_write_b16_d16_hi v90, v83 offset:2368
	v_cvt_pk_bf16_f32 v84, v9, v41
	v_cvt_pk_bf16_f32 v85, v25, v57
; __device__ __forceinline__ void st_bf4(bf16_t* p, const f32x4 v) { u32x2 w; w.x = cvt_pk_bf16(v[0], v[1]); w.y = cvt_pk_bf16(v[2], v[3]); *(u32x2*)p = w; }
; #define LAS __attribute__((address_space(3)))
; #define MFMA16(a, b, c) __builtin_amdgcn_mfma_f32_16x16x32_bf16((a), (b), (c), 0, 0, 0)
; DI float gelu_tanh(float y) { const float z = 1.5957691216057308f * (y + 0.044715f * y * y * y); return y * sigm(z); }
; template <bool OUT>
; DI void s5_tile(const S5C& K, const float* U, int row0, int g, int nruns, int nvalid, float (&hre)[2], float (&him)[2], LAS bf16_t* Hs, const float* dvec, bf16_t* YC0, int lane) {
;     ...
;         const int l15 = lane & 15, quad = lane >> 4;
; #pragma unroll
;         for (int tt = 0; tt < 2; ++tt) {
;             if (tt * 16 < nvalid) {
;                 f32x4 acc = {0.f, 0.f, 0.f, 0.f};
; #pragma unroll
;                 for (int ks = 0; ks < 4; ++ks) { const bf16x8 hf8 = *(const LAS bf16x8*)(Hs + (tt * 16 + l15) * 136 + ks * 32 + quad * 8); acc = MFMA16(K.cf[ks], hf8, acc); }
;                 const int tk = tt * 16 + l15;
;                 if (tk < nvalid) { const size_t ro = (size_t)(row0 + tk) * 512 + g * 16 + quad * 4;
;                     const f32x4 u4 = *(const f32x4*)(U + ro), d4 = *(const f32x4*)(dvec + quad * 4); f32x4 y = acc + d4 * u4;
;                     y[0] = gelu_tanh(y[0]); y[1] = gelu_tanh(y[1]); y[2] = gelu_tanh(y[2]); y[3] = gelu_tanh(y[3]);
;                     st_bf4(YC0 + ro, y); }
;             }
;         }
;     }
; DI void s5_prompt_task(LAS unsigned char* lds, int task, int l, ArgsP a, const float* U, bf16_t* YC0, int tid) {
;     ...
;     for (int tl = 0; tl < 8; ++tl) s5_tile<true>(K, U, rowb + tl * 32, g, 8, 32, hre, him, Hs, dvec, YC0, lane);
;     if (wave == 7 && lane < 32) {
; #pragma unroll
;         for (int st = 0; st < 2; ++st) { a->out[OFF_SRP + ((size_t)(l * 8 + b) * 32 + g) * 64 + st * 32 + lane] = hre[st]; a->out[OFF_SIP + ((size_t)(l * 8 + b) * 32 + g) * 64 + st * 32 + lane] = him[st]; } }
	ds_write_b16 v90, v84 offset:2448
	ds_write_b16_d16_hi v90, v84 offset:2576
	ds_write_b16 v90, v85 offset:2512
	ds_write_b16_d16_hi v90, v85 offset:2640
	v_cvt_pk_bf16_f32 v82, v10, v42
	v_cvt_pk_bf16_f32 v83, v26, v58
	ds_write_b16 v90, v82 offset:2720
	ds_write_b16_d16_hi v90, v82 offset:2848
	ds_write_b16 v90, v83 offset:2784
	ds_write_b16_d16_hi v90, v83 offset:2912
	v_cvt_pk_bf16_f32 v84, v11, v43
	v_cvt_pk_bf16_f32 v85, v27, v59
	ds_write_b16 v90, v84 offset:2992
	ds_write_b16_d16_hi v90, v84 offset:3120
	ds_write_b16 v90, v85 offset:3056
	ds_write_b16_d16_hi v90, v85 offset:3184
	v_cvt_pk_bf16_f32 v82, v12, v44
	v_cvt_pk_bf16_f32 v83, v28, v60
	ds_write_b16 v90, v82 offset:3264
	ds_write_b16_d16_hi v90, v82 offset:3392
	ds_write_b16 v90, v83 offset:3328
	ds_write_b16_d16_hi v90, v83 offset:3456
	v_cvt_pk_bf16_f32 v84, v13, v45
	v_cvt_pk_bf16_f32 v85, v29, v61
	ds_write_b16 v90, v84 offset:3536
	ds_write_b16_d16_hi v90, v84 offset:3664
	ds_write_b16 v90, v85 offset:3600
	ds_write_b16_d16_hi v90, v85 offset:3728
	v_cvt_pk_bf16_f32 v82, v14, v46
	v_cvt_pk_bf16_f32 v83, v30, v62
	ds_write_b16 v90, v82 offset:3808
	ds_write_b16_d16_hi v90, v82 offset:3936
	ds_write_b16 v90, v83 offset:3872
	ds_write_b16_d16_hi v90, v83 offset:4000
	v_cvt_pk_bf16_f32 v84, v15, v47
	v_cvt_pk_bf16_f32 v85, v31, v63
	ds_write_b16 v90, v84 offset:4080
	ds_write_b16_d16_hi v90, v84 offset:4208
	ds_write_b16 v90, v85 offset:4144
	ds_write_b16_d16_hi v90, v85 offset:4272
	ds_read_b128 v[0:3], v94
	ds_read_b128 v[4:7], v94 offset:64
	ds_read_b128 v[8:11], v94 offset:128
	ds_read_b128 v[12:15], v94 offset:192
	ds_read_b128 v[16:19], v94 offset:4352
	ds_read_b128 v[20:23], v94 offset:4416
	ds_read_b128 v[24:27], v94 offset:4480
	ds_read_b128 v[28:31], v94 offset:4544
	s_waitcnt lgkmcnt(7)
	v_mfma_f32_16x16x32_bf16 v[32:35], v[102:105], v[0:3], 0
	s_waitcnt lgkmcnt(6)
	v_mfma_f32_16x16x32_bf16 v[32:35], v[110:113], v[4:7], v[32:35]
	s_waitcnt lgkmcnt(5)
	v_mfma_f32_16x16x32_bf16 v[32:35], v[118:121], v[8:11], v[32:35]
	s_waitcnt lgkmcnt(4)
	v_mfma_f32_16x16x32_bf16 v[32:35], v[126:129], v[12:15], v[32:35]
	s_waitcnt lgkmcnt(3)
	v_mfma_f32_16x16x32_bf16 v[40:43], v[102:105], v[16:19], 0
	s_waitcnt lgkmcnt(2)
	v_mfma_f32_16x16x32_bf16 v[40:43], v[110:113], v[20:23], v[40:43]
	s_waitcnt lgkmcnt(1)
	v_mfma_f32_16x16x32_bf16 v[40:43], v[118:121], v[24:27], v[40:43]
	s_waitcnt lgkmcnt(0)
	v_mfma_f32_16x16x32_bf16 v[40:43], v[126:129], v[28:31], v[40:43]
	s_add_i32 s30, s30, 16
	s_cmpk_eq_i32 s30, 0x80
	s_waitcnt vmcnt(2)
	v_pk_fma_f32 v[32:33], v[214:215], v[222:223], v[32:33]
	v_pk_fma_f32 v[34:35], v[216:217], v[224:225], v[34:35]
	v_mul_f32_e32 v36, 0x3d372713, v32
	v_mul_f32_e32 v37, 0x3d372713, v33
	v_mul_f32_e32 v38, 0x3d372713, v34
	v_mul_f32_e32 v39, 0x3d372713, v35
	v_mul_f32_e32 v36, v32, v36
	v_mul_f32_e32 v37, v33, v37
	v_mul_f32_e32 v38, v34, v38
	v_mul_f32_e32 v39, v35, v39
	v_fma_f32 v36, v32, v36, v32
	v_fma_f32 v37, v33, v37, v33
	v_fma_f32 v38, v34, v38, v34
	v_fma_f32 v39, v35, v39, v35
	v_mul_f32_e32 v36, 0x3fcc422a, v36
	v_mul_f32_e32 v37, 0x3fcc422a, v37
	v_mul_f32_e32 v38, 0x3fcc422a, v38
	v_mul_f32_e32 v39, 0x3fcc422a, v39
	v_mul_f32_e32 v36, 0xbfb8aa3b, v36
	v_mul_f32_e32 v37, 0xbfb8aa3b, v37
	v_mul_f32_e32 v38, 0xbfb8aa3b, v38
	v_mul_f32_e32 v39, 0xbfb8aa3b, v39
	v_exp_f32_e32 v36, v36
	v_exp_f32_e32 v37, v37
	v_exp_f32_e32 v38, v38
	v_exp_f32_e32 v39, v39
	v_add_f32_e32 v36, 1.0, v36
	v_add_f32_e32 v37, 1.0, v37
	v_add_f32_e32 v38, 1.0, v38
	v_add_f32_e32 v39, 1.0, v39
	v_rcp_f32_e32 v36, v36
	v_rcp_f32_e32 v37, v37
	v_rcp_f32_e32 v38, v38
	v_rcp_f32_e32 v39, v39
	v_mul_f32_e32 v36, v32, v36
	v_mul_f32_e32 v37, v33, v37
	v_mul_f32_e32 v38, v34, v38
	v_mul_f32_e32 v39, v35, v39
	v_cvt_pk_bf16_f32 v32, v36, v37
	v_cvt_pk_bf16_f32 v33, v38, v39
	global_store_dwordx2 v[230:231], v[32:33], off
	v_pk_fma_f32 v[40:41], v[218:219], v[222:223], v[40:41]
	v_pk_fma_f32 v[42:43], v[220:221], v[224:225], v[42:43]
	v_mul_f32_e32 v44, 0x3d372713, v40
	v_mul_f32_e32 v45, 0x3d372713, v41
	v_mul_f32_e32 v46, 0x3d372713, v42
	v_mul_f32_e32 v47, 0x3d372713, v43
	v_mul_f32_e32 v44, v40, v44
	v_mul_f32_e32 v45, v41, v45
	v_mul_f32_e32 v46, v42, v46
	v_mul_f32_e32 v47, v43, v47
	v_fma_f32 v44, v40, v44, v40
	v_fma_f32 v45, v41, v45, v41
	v_fma_f32 v46, v42, v46, v42
	v_fma_f32 v47, v43, v47, v43
	v_mul_f32_e32 v44, 0x3fcc422a, v44
	v_mul_f32_e32 v45, 0x3fcc422a, v45
	v_mul_f32_e32 v46, 0x3fcc422a, v46
	v_mul_f32_e32 v47, 0x3fcc422a, v47
	v_mul_f32_e32 v44, 0xbfb8aa3b, v44
	v_mul_f32_e32 v45, 0xbfb8aa3b, v45
	v_mul_f32_e32 v46, 0xbfb8aa3b, v46
	v_mul_f32_e32 v47, 0xbfb8aa3b, v47
	v_exp_f32_e32 v44, v44
	v_exp_f32_e32 v45, v45
	v_exp_f32_e32 v46, v46
	v_exp_f32_e32 v47, v47
	v_add_f32_e32 v44, 1.0, v44
	v_add_f32_e32 v45, 1.0, v45
	v_add_f32_e32 v46, 1.0, v46
	v_add_f32_e32 v47, 1.0, v47
	v_rcp_f32_e32 v44, v44
	v_rcp_f32_e32 v45, v45
	v_rcp_f32_e32 v46, v46
	v_rcp_f32_e32 v47, v47
	v_mul_f32_e32 v44, v40, v44
	v_mul_f32_e32 v45, v41, v45
	v_mul_f32_e32 v46, v42, v46
	v_mul_f32_e32 v47, v43, v47
	v_cvt_pk_bf16_f32 v40, v44, v45
	v_cvt_pk_bf16_f32 v41, v46, v47
	global_store_dwordx2 v[232:233], v[40:41], off
	s_waitcnt vmcnt(2)
	s_cbranch_scc0 .Ls5b_tile
	v_mov_b64_e32 v[82:83], v[66:67]
	v_mov_b64_e32 v[84:85], v[68:69]
	s_nop 1
	v_permlane32_swap_b32_e32 v82, v164
	v_permlane32_swap_b32_e32 v83, v162
	v_permlane32_swap_b32_e32 v84, v165
	v_permlane32_swap_b32_e32 v85, v163
	s_nop 0
